# baseline (speedup 1.0000x reference)
; __device__ __forceinline__ int otid() { int t = threadIdx.x; asm volatile("" : "+v"(t)); return t; }
; __device__ void attn_b_item(const Params& p, int layer, int b, int h, int qblk, unsigned char* smem) {
;     const int tid_ = otid(); const int lane = tid_ & 63, w = tid_ >> 6, l15 = lane & 15, kg = lane >> 4;
;     const bf16_t* proj = reinterpret_cast<const bf16_t*>(p.ws + WS_PROJ) + (size_t)b * SEQ * PW;
;     const bf16_t* kbase = proj + 768 + h * 64;
;     const bf16_t* vbase = reinterpret_cast<const bf16_t*>(p.ws + WS_VT) + ((size_t)b * VTW + 256 + h * 64) * SEQ;
;     const int fo = swz(l15 * 64 + kg * 16);
;     const TileOfs tofs = make_tile_ofs(tid_);
;     const int qw0 = qblk * 256 + w * 32;
;     bf16x8 qf[2][2];
; #pragma unroll
;     for (int c = 0; c < 2; ++c)
; #pragma unroll
;         for (int qt = 0; qt < 2; ++qt)
;             qf[c][qt] = *reinterpret_cast<const bf16x8*>(proj + (size_t)(qw0 + qt * 16 + l15) * PW + 512 + h * 64 + c * 32 + kg * 8);
;     f32x4 o[2][4];
;     float R[2] = {0.f, 0.f};
; #pragma unroll
;     for (int qt = 0; qt < 2; ++qt)
; #pragma unroll
;         for (int et = 0; et < 4; ++et) o[qt][et] = f32x4{0.f, 0.f, 0.f, 0.f};
;     const float c2 = 0.125f * LOG2E;
;     const int gmax = qblk * 8 + w;
;     const int jmax = qblk * 4 + 3;
;     const float RSTOP = -110.f * LOG2E;
;     TileRegs tr;
;     attn_tile_load(tr, kbase, vbase, jmax * 64, tofs);
;     attn_tile_store(tr, smem, tofs);
;     __syncthreads();
.LBB0_409:
	s_and_b64 vcc, exec, s[2:3]
	s_cbranch_vccz .LBB0_430
	v_readfirstlane_b32 s100, v189
	s_lshr_b32 s100, s100, 6
	s_sub_i32 s100, 7, s100
	s_bfe_u32 s30, s28, 0x10002
	s_add_i32 s8, s28, 0xfffffc00
	s_mul_i32 s2, s30, 0x3400000
	s_add_u32 s4, s42, s2
	s_addc_u32 s5, s43, 0
	s_lshl_b32 s2, s28, 6
	s_and_b32 s29, s2, 0xc0
	s_mul_i32 s2, s30, 0x280
	s_add_i32 s2, s2, s29
	v_mov_b32_e32 v0, v189
	s_lshl_b32 s2, s2, 15
	s_add_i32 s2, s2, 0x800000
	v_lshrrev_b32_e32 v20, 3, v0
	s_add_u32 s2, s52, s2
	v_and_b32_e32 v2, 6, v20
	v_lshrrev_b32_e32 v3, 2, v0
	v_ashrrev_i32_e32 v18, 6, v0
	s_addc_u32 s3, s53, 0
	v_and_or_b32 v21, v3, 1, v2
	v_lshrrev_b32_e32 v2, 1, v0
	s_lshl_b32 s6, s8, 5
	v_and_b32_e32 v23, 4, v2
	v_and_b32_e32 v24, 3, v0
	s_and_b32 s6, s6, 0xffffff00
	v_lshlrev_b32_e32 v25, 5, v18
	v_and_b32_e32 v117, 15, v0
	v_or_b32_e32 v2, v23, v24
	v_add_u32_e32 v94, s6, v25
	v_lshlrev_b32_e32 v6, 3, v2
	v_or_b32_e32 v7, v94, v117
	v_mov_b64_e32 v[2:3], s[4:5]
	s_waitcnt lgkmcnt(0)
	v_mad_i64_i32 v[4:5], s[6:7], v7, s48, v[2:3]
	s_lshl_b32 s62, s29, 1
	v_lshl_add_u64 v[10:11], v[4:5], 0, s[62:63]
	v_or_b32_e32 v4, 16, v7
	v_ashrrev_i32_e32 v19, 3, v0
	v_mad_i64_i32 v[2:3], s[6:7], v4, s48, v[2:3]
	s_add_u32 s4, s4, s62
	v_and_or_b32 v22, v19, -8, v21
	s_addc_u32 s5, s5, 0
	s_lshr_b32 s6, s8, 1
	v_lshl_add_u64 v[12:13], v[2:3], 0, s[62:63]
	v_mul_lo_u32 v2, v22, s82
	s_and_b32 s9, s8, -8
	s_or_b32 s8, s6, 3
	v_or_b32_e32 v2, v2, v6
	s_lshl_b32 s62, s8, 6
	s_mul_i32 s6, s8, 0x34000
	s_mul_hi_u32 s7, s62, 0xd00
	s_add_u32 s6, s4, s6
	v_ashrrev_i32_e32 v3, 31, v2
	s_addc_u32 s7, s5, s7
	v_lshlrev_b64 v[14:15], 1, v[2:3]
	v_lshl_or_b32 v6, v22, 14, v6
	v_lshl_add_u64 v[2:3], s[6:7], 0, v[14:15]
	s_lshl_b64 s[6:7], s[62:63], 1
	s_add_u32 s6, s2, s6
	v_ashrrev_i32_e32 v7, 31, v6
	v_bfe_u32 v116, v0, 4, 2
	s_addc_u32 s7, s3, s7
	v_lshlrev_b64 v[16:17], 1, v[6:7]
	v_lshlrev_b32_e32 v92, 4, v116
	v_mov_b32_e32 v93, v1
	global_load_dwordx4 v[2:5], v[2:3], off offset:1536
	v_lshl_add_u64 v[6:7], s[6:7], 0, v[16:17]
	v_lshl_add_u64 v[10:11], v[10:11], 0, v[92:93]
	global_load_dwordx4 v[6:9], v[6:7], off
	v_lshl_add_u64 v[12:13], v[12:13], 0, v[92:93]
	global_load_dwordx4 v[36:39], v[10:11], off offset:1024
	global_load_dwordx4 v[40:43], v[10:11], off offset:1088
	global_load_dwordx4 v[44:47], v[12:13], off offset:1024
	global_load_dwordx4 v[48:51], v[12:13], off offset:1088
	v_lshrrev_b32_e32 v11, 1, v19
	v_and_b32_e32 v11, 12, v11
	v_and_or_b32 v11, v21, 3, v11
	v_lshlrev_b32_e32 v13, 8, v23
	v_lshlrev_b32_e32 v23, 1, v19
	v_lshlrev_b32_e32 v10, 2, v0
	v_lshrrev_b32_e32 v12, 7, v0
	v_lshlrev_b32_e32 v11, 6, v11
	v_lshlrev_b32_e32 v21, 4, v24
	v_and_b32_e32 v23, 32, v23
	v_bfe_u32 v0, v0, 5, 1
	v_bitop3_b32 v11, v11, v23, v21 bitop3:0x36
	v_and_b32_e32 v23, 0x3ffffe, v18
	v_and_or_b32 v0, v12, s94, v0
	v_and_or_b32 v20, v20, 1, v23
	v_lshlrev_b32_e32 v22, 6, v22
	v_lshlrev_b32_e32 v19, 2, v19
	v_lshlrev_b32_e32 v0, 11, v0
	v_and_b32_e32 v10, 32, v10
	v_lshlrev_b32_e32 v20, 10, v20
	v_and_or_b32 v21, v22, s64, v21
	v_and_b32_e32 v19, 32, v19
	v_lshlrev_b32_e32 v96, 3, v116
	v_lshl_or_b32 v22, v117, 6, v92
	v_or3_b32 v93, v0, v13, v11
	v_lshl_add_u64 v[100:101], s[2:3], 0, v[16:17]
	s_movk_i32 s2, 0x2400
	v_or_b32_e32 v0, v25, v117
	v_bitop3_b32 v97, v19, v20, v21 bitop3:0xde
	v_bitop3_b32 v118, v22, s2, v10 bitop3:0xde
	s_movk_i32 s2, 0x1000
	v_sub_u32_e32 v0, v0, v96
	v_add_u32_e32 v95, s9, v18
	v_lshl_add_u64 v[98:99], s[4:5], 0, v[14:15]
	v_bitop3_b32 v119, v22, s2, v10 bitop3:0xde
	v_add_u32_e32 v120, 0xffffff20, v0
	v_lshl_add_u32 v120, s100, 5, v120
	v_add_u32_e32 v121, -7, v18
	v_mov_b32_e32 v0, v1
	s_or_b32 s31, s9, 7
	s_mov_b32 s34, 0
	v_mov_b32_e32 v122, 0
	s_mov_b64 s[22:23], 0
	v_mov_b32_e32 v124, s8
	v_mov_b32_e32 v123, 0
	v_add_u32_e32 v134, 0xfffff000, v119
	v_add_u32_e32 v135, 0xfffffc00, v118
	s_sub_i32 s2, s8, 1
	s_max_i32 s2, s2, 0
	s_lshl_b32 s2, s2, 6
	s_mul_i32 s6, s2, 0xd00
	s_mul_hi_u32 s7, s2, 0xd00
	v_lshl_add_u64 v[136:137], v[98:99], 0, s[6:7]
	global_load_dwordx4 v[60:63], v[136:137], off offset:1536
	s_lshl_b32 s6, s2, 1
	s_mov_b32 s7, 0
	v_lshl_add_u64 v[136:137], v[100:101], 0, s[6:7]
	global_load_dwordx4 v[64:67], v[136:137], off
	s_sub_i32 s2, s8, 2
	s_max_i32 s2, s2, 0
	s_lshl_b32 s2, s2, 6
	s_mul_i32 s6, s2, 0xd00
	s_mul_hi_u32 s7, s2, 0xd00
	v_lshl_add_u64 v[136:137], v[98:99], 0, s[6:7]
	global_load_dwordx4 v[68:71], v[136:137], off offset:1536
	s_lshl_b32 s6, s2, 1
	s_mov_b32 s7, 0
	v_lshl_add_u64 v[136:137], v[100:101], 0, s[6:7]
	global_load_dwordx4 v[72:75], v[136:137], off
	s_sub_i32 s2, s8, 3
	s_max_i32 s2, s2, 0
	s_lshl_b32 s2, s2, 6
	s_mul_i32 s6, s2, 0xd00
	s_mul_hi_u32 s7, s2, 0xd00
	v_lshl_add_u64 v[136:137], v[98:99], 0, s[6:7]
	global_load_dwordx4 v[76:79], v[136:137], off offset:1536
	s_lshl_b32 s6, s2, 1
	s_mov_b32 s7, 0
	v_lshl_add_u64 v[136:137], v[100:101], 0, s[6:7]
	global_load_dwordx4 v[80:83], v[136:137], off
	s_sub_i32 s2, s8, 4
	s_max_i32 s2, s2, 0
	s_lshl_b32 s2, s2, 6
	s_mul_i32 s6, s2, 0xd00
	s_mul_hi_u32 s7, s2, 0xd00
	v_lshl_add_u64 v[136:137], v[98:99], 0, s[6:7]
	global_load_dwordx4 v[84:87], v[136:137], off offset:1536
	s_lshl_b32 s6, s2, 1
	s_mov_b32 s7, 0
	v_lshl_add_u64 v[136:137], v[100:101], 0, s[6:7]
	global_load_dwordx4 v[88:91], v[136:137], off
	s_and_b32 s2, s8, 7
	s_lshl_b32 s2, s2, 14
	v_add_u32_e32 v136, s2, v93
	v_add_u32_e32 v137, s2, v97
	s_waitcnt vmcnt(13)
	ds_write_b128 v136, v[2:5]
	v_mov_b32_e32 v2, v1
	v_mov_b32_e32 v3, v1
	s_waitcnt vmcnt(12)
	ds_write_b128 v137, v[6:9] offset:8192
	s_sub_i32 s2, s8, 1
	s_and_b32 s2, s2, 7
	s_lshl_b32 s2, s2, 14
	v_add_u32_e32 v136, s2, v93
	v_add_u32_e32 v137, s2, v97
	s_waitcnt vmcnt(7)
	ds_write_b128 v136, v[60:63]
	s_waitcnt vmcnt(6)
	ds_write_b128 v137, v[64:67] offset:8192
	s_sub_i32 s2, s8, 2
	s_and_b32 s2, s2, 7
	s_lshl_b32 s2, s2, 14
	v_add_u32_e32 v136, s2, v93
	v_add_u32_e32 v137, s2, v97
	s_waitcnt vmcnt(5)
	ds_write_b128 v136, v[68:71]
	s_waitcnt vmcnt(4)
	ds_write_b128 v137, v[72:75] offset:8192
	s_sub_i32 s2, s8, 3
	s_and_b32 s2, s2, 7
	s_lshl_b32 s2, s2, 14
	v_add_u32_e32 v136, s2, v93
	v_add_u32_e32 v137, s2, v97
	s_waitcnt vmcnt(3)
	ds_write_b128 v136, v[76:79]
	s_waitcnt vmcnt(2)
	ds_write_b128 v137, v[80:83] offset:8192
	s_sub_i32 s2, s8, 4
	s_and_b32 s2, s2, 7
	s_lshl_b32 s2, s2, 14
	v_add_u32_e32 v136, s2, v93
	v_add_u32_e32 v137, s2, v97
	s_waitcnt vmcnt(1)
	ds_write_b128 v136, v[84:87]
	s_waitcnt vmcnt(0)
	ds_write_b128 v137, v[88:91] offset:8192
	v_mov_b64_e32 v[6:7], v[2:3]
	v_mov_b64_e32 v[10:11], v[2:3]
	v_mov_b64_e32 v[14:15], v[2:3]
	v_mov_b64_e32 v[18:19], v[2:3]
	v_mov_b64_e32 v[22:23], v[2:3]
	v_mov_b64_e32 v[26:27], v[2:3]
	v_mov_b64_e32 v[30:31], v[2:3]
	v_mov_b64_e32 v[34:35], v[2:3]
	v_mov_b64_e32 v[4:5], v[0:1]
	v_mov_b64_e32 v[8:9], v[0:1]
	v_mov_b64_e32 v[12:13], v[0:1]
	v_mov_b64_e32 v[16:17], v[0:1]
	v_mov_b64_e32 v[20:21], v[0:1]
	v_mov_b64_e32 v[24:25], v[0:1]
	v_mov_b64_e32 v[28:29], v[0:1]
	v_mov_b64_e32 v[32:33], v[0:1]
	s_waitcnt lgkmcnt(0)
	s_barrier
; __device__ void attn_b_item(const Params& p, int layer, int b, int h, int qblk, unsigned char* smem) {
;     ...
;     for (int j = jmax; j >= 0; --j) {
;         attn_tile_load(tr, kbase, vbase, (j > 0 ? j - 1 : 0) * 64, tofs);
;         const unsigned char* st = smem + sidx * 16384;
; #pragma unroll 1
.LBB0_411:
	v_sub_u32_e64 v0, v124, 5 clamp
	v_lshlrev_b32_e32 v0, 6, v0
	v_mad_u64_u32 v[2:3], s[2:3], v0, s48, v[98:99]
	v_lshl_add_u64 v[56:57], v[0:1], 1, v[100:101]
	global_load_dwordx4 v[52:55], v[2:3], off offset:1536
	s_nop 0
	global_load_dwordx4 v[56:59], v[56:57], off
	s_lshl_b32 s35, s34, 14
	v_or_b32_e32 v0, s35, v118
	v_or_b32_e32 v125, s35, v119
	v_mov_b32_e32 v126, v120
	s_mov_b32 s36, 0
	s_branch .LBB0_414

; __device__ __forceinline__ f32x4 mfma16(bf16x8 a, bf16x8 b, f32x4 c) { return __builtin_amdgcn_mfma_f32_16x16x32_bf16(a, b, c, 0, 0, 0); }
; __device__ __forceinline__ float ex2(float x) { return __builtin_amdgcn_exp2f(x); }
; __device__ __forceinline__ float lg2(float x) { return __builtin_amdgcn_logf(x); }
; __device__ __forceinline__ int otid() { int t = threadIdx.x; asm volatile("" : "+v"(t)); return t; }
; __device__ __forceinline__ void sb_group(const unsigned char* st, int kgp, int fo, const bf16x8 (&qf)[2][2], f32x4 (&o)[2][4], float (&R)[2],
;                                          float c2, int d0, bool masked) {
;     const int kg = (otid() & 63) >> 4;
;     bf16x8 kf[2][2], vf[4];
; #pragma unroll
;     for (int t = 0; t < 2; ++t)
; #pragma unroll
;         for (int c = 0; c < 2; ++c) kf[t][c] = lds_frag(st + ((kgp * 2 + t) * 2 + c) * 1024 + fo);
; #pragma unroll
;     for (int et = 0; et < 4; ++et) vf[et] = lds_frag(st + 8192 + (et * 2 + kgp) * 1024 + fo);
;     const f32x4 zero = {0.f, 0.f, 0.f, 0.f};
; #pragma unroll
;     for (int qt = 0; qt < 2; ++qt) {
;         const int dq = d0 + qt * 16;
;         f32x4 s[2];
; #pragma unroll
;         for (int t = 0; t < 2; ++t) s[t] = mfma16(kf[t][1], qf[1][qt], mfma16(kf[t][0], qf[0][qt], zero));
;         float lb[8], l1[8];
; #pragma unroll
;         for (int j = 0; j < 8; ++j) {
;             const float z2 = s[j >> 2][j & 3] * c2;
;             const float sp = lg2(1.f + ex2(-fabsf(z2)));
;             lb[j] = fminf(z2, 0.f) - sp;
;             l1[j] = lb[j] - z2;
;         }
; __device__ void attn_b_item(const Params& p, int layer, int b, int h, int qblk, unsigned char* smem) {
;     ...
;     for (int j = jmax; j >= 0; --j) {
;         attn_tile_load(tr, kbase, vbase, (j > 0 ? j - 1 : 0) * 64, tofs);
;         const unsigned char* st = smem + sidx * 16384;
; #pragma unroll 1
;     ...
;             const int g = j * 2 + kk;
;             if (g <= gmax && !done) {
;                 const int d0 = (qw0 + l15) - (g * 32 + kg * 8);
;                 sb_group(st, kk, fo, qf, o, R, c2, d0, g == gmax);
;                 done = __all(R[0] < RSTOP && R[1] < RSTOP);
.LBB0_414:
	s_add_i32 s101, s31, s36
	s_sub_i32 s101, s101, s100
	s_cmp_lt_i32 s101, 0
	s_cbranch_scc0 .Lmy_b_ok
	s_mov_b64 s[24:25], exec
	s_branch .LBB0_413
.Lmy_b_ok:
	s_lshr_b32 s2, s101, 1
	s_and_b32 s2, s2, 7
	s_lshl_b32 s2, s2, 14
	s_and_b32 s3, s101, 1
	s_lshl_b32 s6, s3, 12
	s_add_i32 s6, s6, s2
	s_lshl_b32 s3, s3, 10
	s_add_i32 s3, s3, s2
	v_add_u32_e32 v125, s6, v134
	v_add_u32_e32 v0, s3, v135
	v_cmp_le_i32_e32 vcc, s101, v95
	s_xor_b64 s[2:3], s[22:23], -1
	s_andn2_b64 s[4:5], s[22:23], exec
	s_and_b64 s[6:7], s[22:23], exec
	s_and_b64 s[2:3], vcc, s[2:3]
	s_or_b64 s[22:23], s[4:5], s[6:7]
	s_and_saveexec_b64 s[24:25], s[2:3]
	s_cbranch_execz .LBB0_413
	v_mov_b32_e32 v127, v189
	ds_read_b128 v[88:91], v125
	ds_read_b128 v[84:87], v125 offset:1024
	ds_read_b128 v[80:83], v125 offset:2048
	ds_read_b128 v[76:79], v125 offset:3072
	ds_read_b128 v[72:75], v0
	ds_read_b128 v[68:71], v0 offset:2048
	ds_read_b128 v[64:67], v0 offset:4096
	ds_read_b128 v[60:63], v0 offset:6144
	s_waitcnt vmcnt(5) lgkmcnt(7)
	v_mfma_f32_16x16x32_bf16 v[102:105], v[88:91], v[36:39], 0
	v_cmp_eq_u32_e32 vcc, s101, v95
	s_waitcnt vmcnt(4) lgkmcnt(6)
	v_mfma_f32_16x16x32_bf16 v[108:111], v[84:87], v[40:43], v[102:105]
	s_waitcnt lgkmcnt(5)
	v_mfma_f32_16x16x32_bf16 v[102:105], v[80:83], v[36:39], 0
	s_waitcnt lgkmcnt(4)
	v_mfma_f32_16x16x32_bf16 v[112:115], v[76:79], v[40:43], v[102:105]
	s_nop 3
	v_mul_f32_e64 v2, v108, s60
	v_mul_f32_e64 v3, v109, s60
	v_exp_f32_e64 v102, -|v2|
	v_exp_f32_e64 v103, -|v3|
	v_min_f32_e32 v2, 0, v2
	v_min_f32_e32 v3, 0, v3
	v_add_f32_e32 v102, 1.0, v102
	v_add_f32_e32 v103, 1.0, v103
	v_log_f32_e32 v102, v102
	v_log_f32_e32 v103, v103
	s_nop 0
	v_pk_add_f32 v[2:3], v[2:3], v[102:103] neg_lo:[0,1] neg_hi:[0,1]
	v_pk_mul_f32 v[102:103], v[110:111], s[60:61] op_sel_hi:[1,0]
	v_pk_fma_f32 v[108:109], v[108:109], s[60:61], v[2:3] op_sel_hi:[1,0,1] neg_lo:[1,0,0] neg_hi:[1,0,0]
	v_exp_f32_e64 v104, -|v102|
	v_exp_f32_e64 v105, -|v103|
	v_min_f32_e32 v102, 0, v102
	v_min_f32_e32 v103, 0, v103
	v_add_f32_e32 v104, 1.0, v104
	v_add_f32_e32 v105, 1.0, v105
	v_log_f32_e32 v104, v104
	v_log_f32_e32 v105, v105
	s_nop 0
	v_pk_add_f32 v[102:103], v[102:103], v[104:105] neg_lo:[0,1] neg_hi:[0,1]
	v_pk_mul_f32 v[104:105], v[112:113], s[60:61] op_sel_hi:[1,0]
	v_pk_fma_f32 v[110:111], v[110:111], s[60:61], v[102:103] op_sel_hi:[1,0,1] neg_lo:[1,0,0] neg_hi:[1,0,0]
	v_exp_f32_e64 v106, -|v104|
	v_exp_f32_e64 v107, -|v105|
	v_min_f32_e32 v104, 0, v104
	v_min_f32_e32 v105, 0, v105
	v_add_f32_e32 v106, 1.0, v106
	v_add_f32_e32 v107, 1.0, v107
	v_log_f32_e32 v106, v106
	v_log_f32_e32 v107, v107
	s_nop 0
	v_pk_add_f32 v[104:105], v[104:105], v[106:107] neg_lo:[0,1] neg_hi:[0,1]
	v_pk_mul_f32 v[106:107], v[114:115], s[60:61] op_sel_hi:[1,0]
	v_pk_fma_f32 v[112:113], v[112:113], s[60:61], v[104:105] op_sel_hi:[1,0,1] neg_lo:[1,0,0] neg_hi:[1,0,0]
	v_exp_f32_e64 v128, -|v106|
	v_exp_f32_e64 v129, -|v107|
	v_min_f32_e32 v106, 0, v106
	v_min_f32_e32 v107, 0, v107
	v_add_f32_e32 v128, 1.0, v128
	v_add_f32_e32 v129, 1.0, v129
	v_log_f32_e32 v128, v128
	v_log_f32_e32 v129, v129
	s_nop 0
	v_pk_add_f32 v[106:107], v[106:107], v[128:129] neg_lo:[0,1] neg_hi:[0,1]
	s_nop 0
	v_pk_fma_f32 v[114:115], v[114:115], s[60:61], v[106:107] op_sel_hi:[1,0,1] neg_lo:[1,0,0] neg_hi:[1,0,0]
	s_and_saveexec_b64 s[18:19], vcc
	s_cbranch_execz .LBB0_417
	v_cmp_lt_i32_e64 s[14:15], 6, v126
	v_cmp_lt_i32_e64 s[16:17], 7, v126
	v_cmp_lt_i32_e64 s[12:13], 5, v126
	s_or_b64 s[14:15], s[16:17], s[14:15]
	v_cmp_lt_i32_e64 s[10:11], 4, v126
	s_or_b64 s[12:13], s[14:15], s[12:13]
	v_cmp_lt_i32_e64 s[8:9], 3, v126
	s_or_b64 s[10:11], s[12:13], s[10:11]
	v_cmp_lt_i32_e64 s[6:7], 2, v126
	s_or_b64 s[8:9], s[10:11], s[8:9]
	v_cmp_lt_i32_e64 s[4:5], 1, v126
	s_or_b64 s[6:7], s[8:9], s[6:7]
	v_cmp_lt_i32_e64 s[2:3], 0, v126
	s_or_b64 s[4:5], s[6:7], s[4:5]
	s_or_b64 s[2:3], s[4:5], s[2:3]
	v_cndmask_b32_e64 v107, v211, v107, s[16:17]
	v_cndmask_b32_e64 v106, v211, v106, s[14:15]
	v_cndmask_b32_e64 v105, v211, v105, s[12:13]
	v_cndmask_b32_e64 v104, v211, v104, s[10:11]
	v_cndmask_b32_e64 v103, v211, v103, s[8:9]
	v_cndmask_b32_e64 v102, v211, v102, s[6:7]
	v_cndmask_b32_e64 v3, v211, v3, s[4:5]
	v_cndmask_b32_e64 v2, v211, v2, s[2:3]
	v_cndmask_b32_e64 v108, 0, v108, s[2:3]
	v_cndmask_b32_e64 v109, 0, v109, s[4:5]
	v_cndmask_b32_e64 v110, 0, v110, s[6:7]
	v_cndmask_b32_e64 v111, 0, v111, s[8:9]
	v_cndmask_b32_e64 v112, 0, v112, s[10:11]
	v_cndmask_b32_e64 v113, 0, v113, s[12:13]
	v_cndmask_b32_e64 v114, 0, v114, s[14:15]
	v_cndmask_b32_e64 v115, 0, v115, s[16:17]

; __device__ void attn_b_item(const Params& p, int layer, int b, int h, int qblk, unsigned char* smem) {
;     ...
;         if (j > 0) attn_tile_store(tr, smem + (sidx ^ 1) * 16384, tofs);
;         sidx ^= 1;
;         if (block_all(done, smem, j & 1)) break;
.LBB0_419:
	v_subrev_co_u32_e32 v0, vcc, 1, v124
	s_lshr_b32 s2, s31, 1
	s_cmp_lt_i32 s2, 5
	s_cbranch_scc1 .LBB0_421
	s_add_i32 s2, s2, 3
	s_and_b32 s2, s2, 7
	s_lshl_b32 s2, s2, 14
	v_add_u32_e32 v3, s2, v93
	v_add_u32_e32 v2, s2, v97
	s_waitcnt vmcnt(1)
	ds_write_b128 v3, v[52:55]
	s_waitcnt vmcnt(0)
	ds_write_b128 v2, v[56:59] offset:8192
